# ret_scan: eight DPP row-sum chains interleaved stage by stage (no s_nop padding, one exec-masked write region)
# speedup vs baseline: 1.0214x; 1.0007x over previous
.LBB0_199:
	s_or_b64 exec, exec, s[48:49]
	s_mul_i32 s4, s22, 0xab
	s_bfe_u32 s4, s4, 0x70009
	s_mul_i32 s4, s4, 3
	s_sub_i32 s4, s22, s4
	v_cvt_pk_bf16_f32 v58, v58, v59
	v_cvt_pk_bf16_f32 v59, v60, v61
	s_and_b32 s4, s4, 0xff
	ds_write_b64 v116, v[58:59]
	v_ashrrev_i32_e32 v58, 2, v97
	v_lshlrev_b32_e32 v83, 2, v96
	s_mul_i32 s4, s4, 0x8c00
	v_add_u32_e32 v119, v58, v83
	v_lshlrev_b32_e32 v58, 3, v97
	v_add_u32_e32 v62, s4, v168
	v_and_b32_e32 v58, 24, v58
	v_mul_lo_u32 v59, v119, s65
	v_add_u32_e32 v132, v62, v58
	v_add3_u32 v58, v132, v118, v59
	v_lshl_add_u32 v134, v96, 3, v62
	v_add_u32_e32 v62, v144, v108
	ds_read_b64_tr_b16 v[136:137], v58 offset:18432
	ds_read_b64_tr_b16 v[138:139], v58 offset:22784
	ds_read_b64_tr_b16 v[152:153], v58 offset:27136
	ds_read_b64_tr_b16 v[154:155], v58 offset:31488
	ds_read_b128 v[156:159], v62
	v_add_u32_e32 v140, s45, v97
	v_mad_u64_u32 v[160:161], s[4:5], v140, s56, v[134:135]
	ds_read2_b64 v[170:173], v160 offset1:4
	ds_read2_b64 v[174:177], v160 offset0:8 offset1:12
	v_add_u32_e32 v141, v144, v114
	ds_read_b128 v[178:181], v141 offset:1024
	ds_read_b128 v[182:185], v141
	v_add_u32_e32 v142, s43, v97
	v_mad_u64_u32 v[162:163], s[4:5], v142, s56, v[134:135]
	ds_read2_b64 v[186:189], v162 offset1:4
	ds_read2_b64 v[190:193], v162 offset0:8 offset1:12
	v_mad_u64_u32 v[194:195], s[4:5], v119, s56, v[132:133]
	ds_read_b64_tr_b16 v[196:197], v194 offset:9216
	ds_read_b64_tr_b16 v[200:201], v194 offset:9248
	ds_read_b64_tr_b16 v[198:199], v194 offset:11520
	ds_read_b64_tr_b16 v[212:213], v194 offset:13824
	ds_read_b64_tr_b16 v[214:215], v194 offset:16128
	ds_read_b64_tr_b16 v[202:203], v194 offset:11552
	ds_read_b64_tr_b16 v[216:217], v194 offset:13856
	ds_read_b64_tr_b16 v[218:219], v194 offset:16160
	ds_read_b64_tr_b16 v[220:221], v194 offset:9280
	ds_read_b64_tr_b16 v[222:223], v194 offset:11584
	ds_read_b64_tr_b16 v[224:225], v194 offset:13888
	ds_read_b64_tr_b16 v[226:227], v194 offset:16192
	ds_read_b64_tr_b16 v[228:229], v194 offset:9312
	ds_read_b64_tr_b16 v[230:231], v194 offset:11616
	ds_read_b64_tr_b16 v[232:233], v194 offset:13920
	ds_read_b64_tr_b16 v[234:235], v194 offset:16224
	s_waitcnt lgkmcnt(15)
	v_mfma_f32_16x16x32_bf16 v[62:65], v[156:159], v[136:139], v[0:3]
	v_cvt_pk_bf16_f32 v58, v50, v51
	v_cvt_pk_bf16_f32 v59, v52, v53
	v_cvt_pk_bf16_f32 v60, v38, v39
	v_cvt_pk_bf16_f32 v61, v40, v41
	v_cvt_pk_bf16_f32 v120, v42, v43
	v_cvt_pk_bf16_f32 v121, v44, v45
	s_waitcnt lgkmcnt(15)
	v_mfma_f32_16x16x32_bf16 v[62:65], v[170:173], v[58:61], v[62:65]
	v_cvt_pk_bf16_f32 v122, v54, v55
	v_cvt_pk_bf16_f32 v123, v56, v57
	s_waitcnt lgkmcnt(15)
	s_nop 1
	v_mfma_f32_16x16x32_bf16 v[62:65], v[174:177], v[120:123], v[62:65]
	s_waitcnt lgkmcnt(15)
	v_mfma_f32_16x16x32_bf16 v[124:127], v[182:185], v[136:139], v[0:3]
	v_mov_b32_e32 v81, v80
	v_pk_mul_f32 v[52:53], v[80:81], v[52:53]
	v_pk_mul_f32 v[50:51], v[84:85], v[50:51]
	s_waitcnt lgkmcnt(15)
	v_mfma_f32_16x16x32_bf16 v[124:127], v[178:181], v[152:155], v[124:127]
	v_pk_mul_f32 v[40:41], v[80:81], v[40:41]
	v_pk_mul_f32 v[38:39], v[84:85], v[38:39]
	s_waitcnt lgkmcnt(15)
	v_mfma_f32_16x16x32_bf16 v[58:61], v[186:189], v[58:61], v[124:127]
	s_nop 2
	s_waitcnt lgkmcnt(15)
	v_mfma_f32_16x16x32_bf16 v[58:61], v[190:193], v[120:123], v[58:61]
	v_pk_mul_f32 v[44:45], v[80:81], v[44:45]
	v_pk_mul_f32 v[42:43], v[84:85], v[42:43]
	s_waitcnt lgkmcnt(13)
	v_mfma_f32_16x16x32_bf16 v[50:53], v[196:199], v[136:139], v[50:53]
	v_pk_mul_f32 v[56:57], v[80:81], v[56:57]
	s_waitcnt lgkmcnt(11)
	v_mfma_f32_16x16x32_bf16 v[50:53], v[212:215], v[152:155], v[50:53]
	v_pk_mul_f32 v[54:55], v[84:85], v[54:55]
	v_cmp_eq_u32_e32 vcc, 0, v97
	s_waitcnt lgkmcnt(10)
	v_mfma_f32_16x16x32_bf16 v[38:41], v[200:203], v[136:139], v[38:41]
	s_waitcnt lgkmcnt(8)
	v_mfma_f32_16x16x32_bf16 v[38:41], v[216:219], v[152:155], v[38:41]
	s_waitcnt lgkmcnt(6)
	v_mfma_f32_16x16x32_bf16 v[42:45], v[220:223], v[136:139], v[42:45]
	s_waitcnt lgkmcnt(4)
	v_mfma_f32_16x16x32_bf16 v[42:45], v[224:227], v[152:155], v[42:45]
	s_waitcnt lgkmcnt(2)
	v_mfma_f32_16x16x32_bf16 v[54:57], v[228:231], v[136:139], v[54:57]
	s_waitcnt lgkmcnt(0)
	v_mfma_f32_16x16x32_bf16 v[54:57], v[232:235], v[152:155], v[54:57]
	v_mul_f32_e32 v170, v62, v62
	v_mul_f32_e32 v171, v63, v63
	v_mul_f32_e32 v172, v64, v64
	v_mul_f32_e32 v173, v65, v65
	v_mul_f32_e32 v174, v58, v58
	v_mul_f32_e32 v175, v59, v59
	v_mul_f32_e32 v176, v60, v60
	v_mul_f32_e32 v177, v61, v61
	v_mov_b32_e32 v178, v165
	v_mov_b32_e32 v179, v165
	v_mov_b32_e32 v180, v165
	v_mov_b32_e32 v181, v165
	v_mov_b32_e32 v182, v165
	v_mov_b32_e32 v183, v165
	v_mov_b32_e32 v184, v165
	v_mov_b32_e32 v185, v165
	v_add_u32_e32 v66, v83, v112
	v_lshl_add_u32 v66, v66, 2, v143
	v_mov_b32_dpp v178, v170 quad_perm:[1,0,3,2] row_mask:0xf bank_mask:0xf
	v_mov_b32_dpp v179, v171 quad_perm:[1,0,3,2] row_mask:0xf bank_mask:0xf
	v_mov_b32_dpp v180, v172 quad_perm:[1,0,3,2] row_mask:0xf bank_mask:0xf
	v_mov_b32_dpp v181, v173 quad_perm:[1,0,3,2] row_mask:0xf bank_mask:0xf
	v_mov_b32_dpp v182, v174 quad_perm:[1,0,3,2] row_mask:0xf bank_mask:0xf
	v_mov_b32_dpp v183, v175 quad_perm:[1,0,3,2] row_mask:0xf bank_mask:0xf
	v_mov_b32_dpp v184, v176 quad_perm:[1,0,3,2] row_mask:0xf bank_mask:0xf
	v_mov_b32_dpp v185, v177 quad_perm:[1,0,3,2] row_mask:0xf bank_mask:0xf
	v_fmac_f32_e32 v178, v62, v62
	v_fmac_f32_e32 v179, v63, v63
	v_fmac_f32_e32 v180, v64, v64
	v_fmac_f32_e32 v181, v65, v65
	v_fmac_f32_e32 v182, v58, v58
	v_fmac_f32_e32 v183, v59, v59
	v_fmac_f32_e32 v184, v60, v60
	v_fmac_f32_e32 v185, v61, v61
	v_add_f32_dpp v170, v178, v178 quad_perm:[2,3,0,1] row_mask:0xf bank_mask:0xf bound_ctrl:1
	v_add_f32_dpp v171, v179, v179 quad_perm:[2,3,0,1] row_mask:0xf bank_mask:0xf bound_ctrl:1
	v_add_f32_dpp v172, v180, v180 quad_perm:[2,3,0,1] row_mask:0xf bank_mask:0xf bound_ctrl:1
	v_add_f32_dpp v173, v181, v181 quad_perm:[2,3,0,1] row_mask:0xf bank_mask:0xf bound_ctrl:1
	v_add_f32_dpp v174, v182, v182 quad_perm:[2,3,0,1] row_mask:0xf bank_mask:0xf bound_ctrl:1
	v_add_f32_dpp v175, v183, v183 quad_perm:[2,3,0,1] row_mask:0xf bank_mask:0xf bound_ctrl:1
	v_add_f32_dpp v176, v184, v184 quad_perm:[2,3,0,1] row_mask:0xf bank_mask:0xf bound_ctrl:1
	v_add_f32_dpp v177, v185, v185 quad_perm:[2,3,0,1] row_mask:0xf bank_mask:0xf bound_ctrl:1
	v_mov_b32_e32 v178, 0
	v_mov_b32_e32 v179, 0
	v_mov_b32_e32 v180, 0
	v_mov_b32_e32 v181, 0
	v_mov_b32_e32 v182, 0
	v_mov_b32_e32 v183, 0
	v_mov_b32_e32 v184, 0
	v_mov_b32_e32 v185, 0
	v_add_f32_dpp v170, v170, v170 row_half_mirror row_mask:0xf bank_mask:0xf bound_ctrl:1
	v_add_f32_dpp v171, v171, v171 row_half_mirror row_mask:0xf bank_mask:0xf bound_ctrl:1
	v_add_f32_dpp v172, v172, v172 row_half_mirror row_mask:0xf bank_mask:0xf bound_ctrl:1
	v_add_f32_dpp v173, v173, v173 row_half_mirror row_mask:0xf bank_mask:0xf bound_ctrl:1
	v_add_f32_dpp v174, v174, v174 row_half_mirror row_mask:0xf bank_mask:0xf bound_ctrl:1
	v_add_f32_dpp v175, v175, v175 row_half_mirror row_mask:0xf bank_mask:0xf bound_ctrl:1
	v_add_f32_dpp v176, v176, v176 row_half_mirror row_mask:0xf bank_mask:0xf bound_ctrl:1
	v_add_f32_dpp v177, v177, v177 row_half_mirror row_mask:0xf bank_mask:0xf bound_ctrl:1
	v_mov_b32_dpp v178, v170 row_mirror row_mask:0xf bank_mask:0xf
	v_mov_b32_dpp v179, v171 row_mirror row_mask:0xf bank_mask:0xf
	v_mov_b32_dpp v180, v172 row_mirror row_mask:0xf bank_mask:0xf
	v_mov_b32_dpp v181, v173 row_mirror row_mask:0xf bank_mask:0xf
	v_mov_b32_dpp v182, v174 row_mirror row_mask:0xf bank_mask:0xf
	v_mov_b32_dpp v183, v175 row_mirror row_mask:0xf bank_mask:0xf
	v_mov_b32_dpp v184, v176 row_mirror row_mask:0xf bank_mask:0xf
	v_mov_b32_dpp v185, v177 row_mirror row_mask:0xf bank_mask:0xf
	s_and_saveexec_b64 s[4:5], vcc
	v_add_f32_e32 v170, v170, v178
	v_add_f32_e32 v171, v171, v179
	v_add_f32_e32 v172, v172, v180
	v_add_f32_e32 v173, v173, v181
	v_add_f32_e32 v174, v174, v182
	v_add_f32_e32 v175, v175, v183
	v_add_f32_e32 v176, v176, v184
	v_add_f32_e32 v177, v177, v185
	ds_write_b32 v66, v170
	ds_write_b32 v66, v171 offset:4
	ds_write_b32 v66, v172 offset:8
	ds_write_b32 v66, v173 offset:12
	ds_write_b32 v66, v174 offset:64
	ds_write_b32 v66, v175 offset:68
	ds_write_b32 v66, v176 offset:72
	ds_write_b32 v66, v177 offset:76
	s_or_b64 exec, exec, s[4:5]
	s_add_i32 s23, s22, 2
	s_cmp_lt_u32 s22, 30
	s_cselect_b64 s[50:51], -1, 0
	s_cmp_gt_u32 s22, 29
	s_cselect_b64 s[48:49], -1, 0
	s_and_b64 vcc, exec, s[48:49]
	v_lshlrev_b32_e32 v119, 1, v164
	s_cbranch_vccnz .LBB0_217
	s_mul_i32 s4, s23, 0xab
	s_bfe_u32 s4, s4, 0x70009
	s_mul_i32 s4, s4, 3
	s_sub_i32 s4, s23, s4
	s_and_b32 s4, s4, 0xff
	s_mul_i32 s4, s4, 0x8c00
	v_add_u32_e32 v66, s4, v76
	v_lshl_add_u32 v67, v106, 1, v66
	v_add3_u32 v66, v66, v77, v119
	s_cmp_eq_u32 s22, 0
	s_cbranch_scc0 .Lrv_b1_n0
	s_waitcnt vmcnt(4)
	s_branch .Lrv_b1_end

.LBB0_227:
	s_bfe_u32 s4, s37, 0x70009
	s_mul_i32 s4, s4, 3
	s_sub_i32 s4, s36, s4
	s_and_b32 s4, s4, 0xff
	v_ashrrev_i32_e32 v58, 2, v121
	v_lshlrev_b32_e32 v83, 2, v120
	s_mul_i32 s4, s4, 0x8c00
	v_add_u32_e32 v95, v58, v83
	v_lshlrev_b32_e32 v58, 3, v121
	v_add_u32_e32 v62, s4, v168
	v_and_b32_e32 v58, 24, v58
	v_mul_lo_u32 v59, v95, s65
	v_add_u32_e32 v94, v62, v58
	v_add3_u32 v58, v94, v118, v59
	v_lshl_add_u32 v130, v120, 3, v62
	v_add_u32_e32 v62, v145, v108
	ds_read_b64_tr_b16 v[136:137], v58 offset:18432
	ds_read_b64_tr_b16 v[138:139], v58 offset:22784
	ds_read_b64_tr_b16 v[152:153], v58 offset:27136
	ds_read_b64_tr_b16 v[154:155], v58 offset:31488
	ds_read_b128 v[156:159], v62
	v_add_u32_e32 v140, s45, v121
	v_mad_u64_u32 v[160:161], s[4:5], v140, s56, v[130:131]
	ds_read2_b64 v[170:173], v160 offset1:4
	ds_read2_b64 v[174:177], v160 offset0:8 offset1:12
	v_add_u32_e32 v141, v145, v114
	ds_read_b128 v[178:181], v141 offset:1024
	ds_read_b128 v[182:185], v141
	v_add_u32_e32 v142, s43, v121
	v_mad_u64_u32 v[162:163], s[4:5], v142, s56, v[130:131]
	v_mad_u64_u32 v[186:187], s[4:5], v95, s56, v[94:95]
	ds_read2_b64 v[188:191], v162 offset1:4
	ds_read2_b64 v[192:195], v162 offset0:8 offset1:12
	ds_read_b64_tr_b16 v[196:197], v186 offset:9216
	ds_read_b64_tr_b16 v[200:201], v186 offset:9248
	ds_read_b64_tr_b16 v[198:199], v186 offset:11520
	ds_read_b64_tr_b16 v[212:213], v186 offset:13824
	ds_read_b64_tr_b16 v[214:215], v186 offset:16128
	ds_read_b64_tr_b16 v[202:203], v186 offset:11552
	ds_read_b64_tr_b16 v[216:217], v186 offset:13856
	ds_read_b64_tr_b16 v[218:219], v186 offset:16160
	ds_read_b64_tr_b16 v[220:221], v186 offset:9280
	ds_read_b64_tr_b16 v[222:223], v186 offset:11584
	ds_read_b64_tr_b16 v[224:225], v186 offset:13888
	ds_read_b64_tr_b16 v[226:227], v186 offset:16192
	ds_read_b64_tr_b16 v[228:229], v186 offset:9312
	ds_read_b64_tr_b16 v[230:231], v186 offset:11616
	ds_read_b64_tr_b16 v[232:233], v186 offset:13920
	ds_read_b64_tr_b16 v[234:235], v186 offset:16224
	s_waitcnt lgkmcnt(15)
	v_mfma_f32_16x16x32_bf16 v[62:65], v[156:159], v[136:139], v[0:3]
	v_cvt_pk_bf16_f32 v58, v50, v51
	v_cvt_pk_bf16_f32 v59, v52, v53
	v_cvt_pk_bf16_f32 v60, v38, v39
	v_cvt_pk_bf16_f32 v61, v40, v41
	v_cvt_pk_bf16_f32 v98, v42, v43
	v_cvt_pk_bf16_f32 v99, v44, v45
	s_waitcnt lgkmcnt(15)
	v_mfma_f32_16x16x32_bf16 v[62:65], v[170:173], v[58:61], v[62:65]
	v_cvt_pk_bf16_f32 v100, v54, v55
	v_cvt_pk_bf16_f32 v101, v56, v57
	s_waitcnt lgkmcnt(15)
	s_nop 1
	v_mfma_f32_16x16x32_bf16 v[62:65], v[174:177], v[98:101], v[62:65]
	s_waitcnt lgkmcnt(15)
	v_mfma_f32_16x16x32_bf16 v[122:125], v[182:185], v[136:139], v[0:3]
	v_mov_b32_e32 v81, v80
	s_waitcnt lgkmcnt(15)
	v_mfma_f32_16x16x32_bf16 v[122:125], v[178:181], v[152:155], v[122:125]
	v_pk_mul_f32 v[52:53], v[80:81], v[52:53]
	v_pk_mul_f32 v[50:51], v[84:85], v[50:51]
	s_waitcnt lgkmcnt(15)
	v_mfma_f32_16x16x32_bf16 v[58:61], v[188:191], v[58:61], v[122:125]
	s_nop 2
	v_pk_mul_f32 v[40:41], v[80:81], v[40:41]
	v_pk_mul_f32 v[38:39], v[84:85], v[38:39]
	s_waitcnt lgkmcnt(15)
	v_mfma_f32_16x16x32_bf16 v[58:61], v[192:195], v[98:101], v[58:61]
	v_pk_mul_f32 v[44:45], v[80:81], v[44:45]
	v_pk_mul_f32 v[42:43], v[84:85], v[42:43]
	s_waitcnt lgkmcnt(13)
	v_mfma_f32_16x16x32_bf16 v[50:53], v[196:199], v[136:139], v[50:53]
	v_pk_mul_f32 v[56:57], v[80:81], v[56:57]
	s_waitcnt lgkmcnt(11)
	v_mfma_f32_16x16x32_bf16 v[50:53], v[212:215], v[152:155], v[50:53]
	v_pk_mul_f32 v[54:55], v[84:85], v[54:55]
	v_cmp_eq_u32_e32 vcc, 0, v121
	s_waitcnt lgkmcnt(10)
	v_mfma_f32_16x16x32_bf16 v[38:41], v[200:203], v[136:139], v[38:41]
	s_waitcnt lgkmcnt(8)
	v_mfma_f32_16x16x32_bf16 v[38:41], v[216:219], v[152:155], v[38:41]
	s_waitcnt lgkmcnt(6)
	v_mfma_f32_16x16x32_bf16 v[42:45], v[220:223], v[136:139], v[42:45]
	s_waitcnt lgkmcnt(4)
	v_mfma_f32_16x16x32_bf16 v[42:45], v[224:227], v[152:155], v[42:45]
	s_waitcnt lgkmcnt(2)
	v_mfma_f32_16x16x32_bf16 v[54:57], v[228:231], v[136:139], v[54:57]
	s_waitcnt lgkmcnt(0)
	v_mfma_f32_16x16x32_bf16 v[54:57], v[232:235], v[152:155], v[54:57]
	v_mul_f32_e32 v170, v62, v62
	v_mul_f32_e32 v171, v63, v63
	v_mul_f32_e32 v172, v64, v64
	v_mul_f32_e32 v173, v65, v65
	v_mul_f32_e32 v174, v58, v58
	v_mul_f32_e32 v175, v59, v59
	v_mul_f32_e32 v176, v60, v60
	v_mul_f32_e32 v177, v61, v61
	v_mov_b32_e32 v178, v165
	v_mov_b32_e32 v179, v165
	v_mov_b32_e32 v180, v165
	v_mov_b32_e32 v181, v165
	v_mov_b32_e32 v182, v165
	v_mov_b32_e32 v183, v165
	v_mov_b32_e32 v184, v165
	v_mov_b32_e32 v185, v165
	v_add_u32_e32 v66, v83, v112
	v_lshl_add_u32 v66, v66, 2, v147
	v_mov_b32_dpp v178, v170 quad_perm:[1,0,3,2] row_mask:0xf bank_mask:0xf
	v_mov_b32_dpp v179, v171 quad_perm:[1,0,3,2] row_mask:0xf bank_mask:0xf
	v_mov_b32_dpp v180, v172 quad_perm:[1,0,3,2] row_mask:0xf bank_mask:0xf
	v_mov_b32_dpp v181, v173 quad_perm:[1,0,3,2] row_mask:0xf bank_mask:0xf
	v_mov_b32_dpp v182, v174 quad_perm:[1,0,3,2] row_mask:0xf bank_mask:0xf
	v_mov_b32_dpp v183, v175 quad_perm:[1,0,3,2] row_mask:0xf bank_mask:0xf
	v_mov_b32_dpp v184, v176 quad_perm:[1,0,3,2] row_mask:0xf bank_mask:0xf
	v_mov_b32_dpp v185, v177 quad_perm:[1,0,3,2] row_mask:0xf bank_mask:0xf
	v_fmac_f32_e32 v178, v62, v62
	v_fmac_f32_e32 v179, v63, v63
	v_fmac_f32_e32 v180, v64, v64
	v_fmac_f32_e32 v181, v65, v65
	v_fmac_f32_e32 v182, v58, v58
	v_fmac_f32_e32 v183, v59, v59
	v_fmac_f32_e32 v184, v60, v60
	v_fmac_f32_e32 v185, v61, v61
	v_add_f32_dpp v170, v178, v178 quad_perm:[2,3,0,1] row_mask:0xf bank_mask:0xf bound_ctrl:1
	v_add_f32_dpp v171, v179, v179 quad_perm:[2,3,0,1] row_mask:0xf bank_mask:0xf bound_ctrl:1
	v_add_f32_dpp v172, v180, v180 quad_perm:[2,3,0,1] row_mask:0xf bank_mask:0xf bound_ctrl:1
	v_add_f32_dpp v173, v181, v181 quad_perm:[2,3,0,1] row_mask:0xf bank_mask:0xf bound_ctrl:1
	v_add_f32_dpp v174, v182, v182 quad_perm:[2,3,0,1] row_mask:0xf bank_mask:0xf bound_ctrl:1
	v_add_f32_dpp v175, v183, v183 quad_perm:[2,3,0,1] row_mask:0xf bank_mask:0xf bound_ctrl:1
	v_add_f32_dpp v176, v184, v184 quad_perm:[2,3,0,1] row_mask:0xf bank_mask:0xf bound_ctrl:1
	v_add_f32_dpp v177, v185, v185 quad_perm:[2,3,0,1] row_mask:0xf bank_mask:0xf bound_ctrl:1
	v_mov_b32_e32 v178, 0
	v_mov_b32_e32 v179, 0
	v_mov_b32_e32 v180, 0
	v_mov_b32_e32 v181, 0
	v_mov_b32_e32 v182, 0
	v_mov_b32_e32 v183, 0
	v_mov_b32_e32 v184, 0
	v_mov_b32_e32 v185, 0
	v_add_f32_dpp v170, v170, v170 row_half_mirror row_mask:0xf bank_mask:0xf bound_ctrl:1
	v_add_f32_dpp v171, v171, v171 row_half_mirror row_mask:0xf bank_mask:0xf bound_ctrl:1
	v_add_f32_dpp v172, v172, v172 row_half_mirror row_mask:0xf bank_mask:0xf bound_ctrl:1
	v_add_f32_dpp v173, v173, v173 row_half_mirror row_mask:0xf bank_mask:0xf bound_ctrl:1
	v_add_f32_dpp v174, v174, v174 row_half_mirror row_mask:0xf bank_mask:0xf bound_ctrl:1
	v_add_f32_dpp v175, v175, v175 row_half_mirror row_mask:0xf bank_mask:0xf bound_ctrl:1
	v_add_f32_dpp v176, v176, v176 row_half_mirror row_mask:0xf bank_mask:0xf bound_ctrl:1
	v_add_f32_dpp v177, v177, v177 row_half_mirror row_mask:0xf bank_mask:0xf bound_ctrl:1
	v_mov_b32_dpp v178, v170 row_mirror row_mask:0xf bank_mask:0xf
	v_mov_b32_dpp v179, v171 row_mirror row_mask:0xf bank_mask:0xf
	v_mov_b32_dpp v180, v172 row_mirror row_mask:0xf bank_mask:0xf
	v_mov_b32_dpp v181, v173 row_mirror row_mask:0xf bank_mask:0xf
	v_mov_b32_dpp v182, v174 row_mirror row_mask:0xf bank_mask:0xf
	v_mov_b32_dpp v183, v175 row_mirror row_mask:0xf bank_mask:0xf
	v_mov_b32_dpp v184, v176 row_mirror row_mask:0xf bank_mask:0xf
	v_mov_b32_dpp v185, v177 row_mirror row_mask:0xf bank_mask:0xf
	s_and_saveexec_b64 s[4:5], vcc
	v_add_f32_e32 v170, v170, v178
	v_add_f32_e32 v171, v171, v179
	v_add_f32_e32 v172, v172, v180
	v_add_f32_e32 v173, v173, v181
	v_add_f32_e32 v174, v174, v182
	v_add_f32_e32 v175, v175, v183
	v_add_f32_e32 v176, v176, v184
	v_add_f32_e32 v177, v177, v185
	ds_write_b32 v66, v170
	ds_write_b32 v66, v171 offset:4
	ds_write_b32 v66, v172 offset:8
	ds_write_b32 v66, v173 offset:12
	ds_write_b32 v66, v174 offset:64
	ds_write_b32 v66, v175 offset:68
	ds_write_b32 v66, v176 offset:72
	ds_write_b32 v66, v177 offset:76
	s_or_b64 exec, exec, s[4:5]
	s_andn2_b64 vcc, exec, s[46:47]
	s_cbranch_vccnz .LBB0_190
	s_add_i32 s4, s22, 3
	s_and_b32 s5, s4, 0xff
	s_mulk_i32 s5, 0xab
	s_bfe_u32 s5, s5, 0x70009
	s_mul_i32 s5, s5, 3
	s_sub_i32 s4, s4, s5
	s_and_b32 s4, s4, 0xff
	s_mul_i32 s4, s4, 0x8c00
	v_add_u32_e32 v66, s4, v76
	v_lshl_add_u32 v67, v106, 1, v66
	v_add3_u32 v66, v66, v77, v119
	s_cmp_eq_u32 s22, 28
	s_cbranch_scc0 .Lrv_b2_n0
	s_waitcnt vmcnt(2)
	s_branch .Lrv_b2_end
